# FOLD tile rewrite + final phase: each group finishes its own rows (no cross-group hand-off)
# baseline (speedup 1.0000x reference)
; __global__ void __launch_bounds__(512, 2) mk_fwd(Args a) {
;     ...
;     if (((blockIdx.x >> 2) & 1) == 1) {
;         if (threadIdx.x == 0) __hip_atomic_fetch_add((unsigned*)(ws + WS_CTL) + 3 * 4096 + 64, 1u, __ATOMIC_RELAXED, __HIP_MEMORY_SCOPE_AGENT);
;         { GV(); rows_resnorm<1, false>(FB, OG, a.in[21], 0.5f, OUTF, nullptr, nullptr, (int)blockIdx.x, G, TG); }
;     } else {
;         { GV(); rows_resnorm<1, false>(FB, OG, a.in[21], 0.5f, OUTF, nullptr, nullptr, gi, GG, TG); }
;         if (threadIdx.x == 0) { unsigned sp = 0; while (__hip_atomic_load((unsigned*)(ws + WS_CTL) + 3 * 4096 + 64, __ATOMIC_RELAXED, __HIP_MEMORY_SCOPE_AGENT) < (unsigned)GG && ++sp < (1u << 22)) __builtin_amdgcn_s_sleep(2);
;             __builtin_amdgcn_fence(__ATOMIC_ACQUIRE, "agent"); asm volatile("s_waitcnt vmcnt(0)" ::: "memory"); }
;         __syncthreads();
;         { const size_t R1_ = (size_t)TG * DM;
;           rows_resnorm<1, false>((bf16_t*)(ws + WS_F) + R1_, (bf16_t*)(ws + WS_OG) + R1_, a.in[21], 0.5f, a.out + R1_, nullptr, nullptr, (int)blockIdx.x, G, TG); }
;     }
.LBB0_1335:
	s_or_b64 exec, exec, s[0:1]
	s_andn2_b64 vcc, exec, s[74:75]
	s_mov_b64 s[0:1], -1
	s_waitcnt lgkmcnt(0)
	s_barrier
	s_branch .LBB0_1343

; __global__ void __launch_bounds__(512, 2) mk_fwd(Args a) {
;     ...
;     } else {
;         { GV(); rows_resnorm<1, false>(FB, OG, a.in[21], 0.5f, OUTF, nullptr, nullptr, gi, GG, TG); }
;         if (threadIdx.x == 0) { unsigned sp = 0; while (__hip_atomic_load((unsigned*)(ws + WS_CTL) + 3 * 4096 + 64, __ATOMIC_RELAXED, __HIP_MEMORY_SCOPE_AGENT) < (unsigned)GG && ++sp < (1u << 22)) __builtin_amdgcn_s_sleep(2);
;             __builtin_amdgcn_fence(__ATOMIC_ACQUIRE, "agent"); asm volatile("s_waitcnt vmcnt(0)" ::: "memory"); }
;         __syncthreads();
;         { const size_t R1_ = (size_t)TG * DM;
;           rows_resnorm<1, false>((bf16_t*)(ws + WS_F) + R1_, (bf16_t*)(ws + WS_OG) + R1_, a.in[21], 0.5f, a.out + R1_, nullptr, nullptr, (int)blockIdx.x, G, TG); }
;     }
.LBB0_1347:
	s_or_b64 exec, exec, s[0:1]
.LBB0_1363:
	s_endpgm
